# grid barrier: non-leader workgroups poll the global release generation directly (one polling hop less), leader releases before its own invalidate
# speedup vs baseline: 1.0077x; 1.0055x over previous
; __device__ __forceinline__ unsigned xb_ld(unsigned* p)              { return __hip_atomic_load(p, __ATOMIC_RELAXED, __HIP_MEMORY_SCOPE_AGENT); }
; __device__ __forceinline__ unsigned xb_add(unsigned* p, unsigned v) { return __hip_atomic_fetch_add(p, v, __ATOMIC_RELAXED, __HIP_MEMORY_SCOPE_AGENT); }
; #define XB_SPIN(cond, bar) do { unsigned _sp = 0; while (cond) { __builtin_amdgcn_s_sleep(1); \
;     if ((++_sp & 255u) == 0u) { if (xb_ld(&(bar)[XB_TMO])) break; if (_sp > XB_SPIN_CAP) { atomicAdd(&(bar)[XB_TMO], 1u); break; } } } } while (0)
; __device__ __forceinline__ void xcd_barrier(const XcdBarrier& b, const bool leader) {
;     ...
;         const unsigned old = xb_add(&bar[XB_XSUB(b.x)], 1u);
;         const unsigned gen = old / nloc;
;         if (old + 1u == (gen + 1u) * nloc) {
;             __builtin_amdgcn_fence(__ATOMIC_RELEASE, "agent");
;             asm volatile("s_waitcnt vmcnt(0)" ::: "memory");
;             const unsigned og = xb_add(&bar[XB_TOP], 1u);
;             const unsigned tg = og / nx;
;             if (og + 1u == (tg + 1u) * nx) xb_add(&bar[XB_TOPGEN], 1u);
;             else XB_SPIN(xb_ld(&bar[XB_TOPGEN]) == tg, bar);
;             __builtin_amdgcn_fence(__ATOMIC_ACQUIRE, "agent");
;             xb_add(&bar[XB_XGEN(b.x)], 1u);
;             asm volatile("s_waitcnt vmcnt(0)" ::: "memory");
;         } else {
;             XB_SPIN(xb_ld(&bar[XB_XGEN(b.x)]) == gen, bar);
.LBB0_49:
	s_or_b64 exec, exec, s[10:11]
	v_cvt_f32_u32_e32 v6, v4
	s_waitcnt vmcnt(0)
	v_readfirstlane_b32 s1, v5
	v_sub_u32_e32 v5, 0, v4
	v_rcp_iflag_f32_e32 v6, v6
	v_add_u32_e32 v7, s1, v3
	v_mul_f32_e32 v6, 0x4f7ffffe, v6
	v_cvt_u32_f32_e32 v6, v6
	v_mul_lo_u32 v3, v5, v6
	v_mul_hi_u32 v3, v6, v3
	v_add_u32_e32 v3, v6, v3
	v_mul_hi_u32 v3, v7, v3
	v_mul_lo_u32 v5, v3, v4
	v_sub_u32_e32 v5, v7, v5
	v_add_u32_e32 v6, 1, v3
	v_cmp_ge_u32_e32 vcc, v5, v4
	s_nop 1
	v_cndmask_b32_e32 v3, v3, v6, vcc
	v_sub_u32_e32 v6, v5, v4
	v_cndmask_b32_e32 v5, v5, v6, vcc
	v_add_u32_e32 v6, 1, v3
	v_cmp_ge_u32_e32 vcc, v5, v4
	v_add_u32_e32 v5, 1, v7
	s_nop 0
	v_cndmask_b32_e32 v3, v3, v6, vcc
	v_mul_lo_u32 v6, v4, v3
	v_add_u32_e32 v4, v6, v4
	v_cmp_ne_u32_e32 vcc, v5, v4
	s_and_saveexec_b64 s[2:3], vcc
	s_xor_b64 s[8:9], exec, s[2:3]
	s_cbranch_execz .LBB0_63
	s_waitcnt lgkmcnt(0)
	v_mov_b32_e32 v2, 0x2000
	s_load_dwordx2 s[14:15], s[90:91], 0xb0
	s_waitcnt lgkmcnt(0)
	s_add_u32 s14, s14, 0x1d79b500
	s_addc_u32 s15, s15, 0
	v_mov_b32_e32 v2, 0
	global_load_dword v2, v2, s[14:15] sc1
	s_waitcnt vmcnt(0)
	v_cmp_eq_u32_e32 vcc, v2, v3
	s_and_saveexec_b64 s[10:11], vcc
	s_cbranch_execz .LBB0_62
	s_load_dwordx4 s[16:19], s[90:91], 0xa8
	s_mov_b32 s1, 1
	s_waitcnt lgkmcnt(0)
	s_mov_b64 s[16:17], 0
	v_mov_b32_e32 v2, 0
	s_add_u32 s12, s18, 0x1d798200
	s_addc_u32 s13, s19, 0
	s_branch .LBB0_53

; __device__ __forceinline__ unsigned xb_ld(unsigned* p)              { return __hip_atomic_load(p, __ATOMIC_RELAXED, __HIP_MEMORY_SCOPE_AGENT); }
; __device__ __forceinline__ unsigned xb_add(unsigned* p, unsigned v) { return __hip_atomic_fetch_add(p, v, __ATOMIC_RELAXED, __HIP_MEMORY_SCOPE_AGENT); }
; #define XB_SPIN(cond, bar) do { unsigned _sp = 0; while (cond) { __builtin_amdgcn_s_sleep(1); \
;     if ((++_sp & 255u) == 0u) { if (xb_ld(&(bar)[XB_TMO])) break; if (_sp > XB_SPIN_CAP) { atomicAdd(&(bar)[XB_TMO], 1u); break; } } } } while (0)
; __device__ __forceinline__ void xcd_barrier(const XcdBarrier& b, const bool leader) {
;     ...
;         const unsigned old = xb_add(&bar[XB_XSUB(b.x)], 1u);
;         const unsigned gen = old / nloc;
;         if (old + 1u == (gen + 1u) * nloc) {
;             __builtin_amdgcn_fence(__ATOMIC_RELEASE, "agent");
;             asm volatile("s_waitcnt vmcnt(0)" ::: "memory");
;             const unsigned og = xb_add(&bar[XB_TOP], 1u);
;             const unsigned tg = og / nx;
;             if (og + 1u == (tg + 1u) * nx) xb_add(&bar[XB_TOPGEN], 1u);
;             else XB_SPIN(xb_ld(&bar[XB_TOPGEN]) == tg, bar);
;             __builtin_amdgcn_fence(__ATOMIC_ACQUIRE, "agent");
;             xb_add(&bar[XB_XGEN(b.x)], 1u);
;             asm volatile("s_waitcnt vmcnt(0)" ::: "memory");
;         } else {
;             XB_SPIN(xb_ld(&bar[XB_XGEN(b.x)]) == gen, bar);
.LBB0_207:
	s_or_b64 exec, exec, s[10:11]
	v_cvt_f32_u32_e32 v6, v4
	s_waitcnt vmcnt(0)
	v_readfirstlane_b32 s1, v5
	v_sub_u32_e32 v5, 0, v4
	v_rcp_iflag_f32_e32 v6, v6
	v_add_u32_e32 v7, s1, v3
	v_mul_f32_e32 v6, 0x4f7ffffe, v6
	v_cvt_u32_f32_e32 v6, v6
	v_mul_lo_u32 v3, v5, v6
	v_mul_hi_u32 v3, v6, v3
	v_add_u32_e32 v3, v6, v3
	v_mul_hi_u32 v3, v7, v3
	v_mul_lo_u32 v5, v3, v4
	v_sub_u32_e32 v5, v7, v5
	v_add_u32_e32 v6, 1, v3
	v_cmp_ge_u32_e32 vcc, v5, v4
	s_nop 1
	v_cndmask_b32_e32 v3, v3, v6, vcc
	v_sub_u32_e32 v6, v5, v4
	v_cndmask_b32_e32 v5, v5, v6, vcc
	v_add_u32_e32 v6, 1, v3
	v_cmp_ge_u32_e32 vcc, v5, v4
	v_add_u32_e32 v5, 1, v7
	s_nop 0
	v_cndmask_b32_e32 v3, v3, v6, vcc
	v_mul_lo_u32 v6, v4, v3
	v_add_u32_e32 v4, v6, v4
	v_cmp_ne_u32_e32 vcc, v5, v4
	s_and_saveexec_b64 s[2:3], vcc
	s_xor_b64 s[8:9], exec, s[2:3]
	s_cbranch_execz .LBB0_221
	s_waitcnt lgkmcnt(0)
	v_mov_b32_e32 v2, 0x2000
	s_load_dwordx2 s[16:17], s[90:91], 0xb0
	s_waitcnt lgkmcnt(0)
	s_add_u32 s16, s16, 0x1d79b500
	s_addc_u32 s17, s17, 0
	v_mov_b32_e32 v2, 0
	global_load_dword v2, v2, s[16:17] sc1
	s_waitcnt vmcnt(0)
	v_cmp_eq_u32_e32 vcc, v2, v3
	s_and_saveexec_b64 s[10:11], vcc
	s_cbranch_execz .LBB0_220
	s_add_u32 s14, s12, 0x1d798200
	s_addc_u32 s15, s13, 0
	s_mov_b32 s1, 1
	s_mov_b64 s[18:19], 0
	v_mov_b32_e32 v2, 0
	s_branch .LBB0_211

; __device__ __forceinline__ unsigned xb_ld(unsigned* p)              { return __hip_atomic_load(p, __ATOMIC_RELAXED, __HIP_MEMORY_SCOPE_AGENT); }
; __device__ __forceinline__ unsigned xb_add(unsigned* p, unsigned v) { return __hip_atomic_fetch_add(p, v, __ATOMIC_RELAXED, __HIP_MEMORY_SCOPE_AGENT); }
; #define XB_SPIN(cond, bar) do { unsigned _sp = 0; while (cond) { __builtin_amdgcn_s_sleep(1); \
;     if ((++_sp & 255u) == 0u) { if (xb_ld(&(bar)[XB_TMO])) break; if (_sp > XB_SPIN_CAP) { atomicAdd(&(bar)[XB_TMO], 1u); break; } } } } while (0)
; __device__ __forceinline__ void xcd_barrier(const XcdBarrier& b, const bool leader) {
;     ...
;         const unsigned old = xb_add(&bar[XB_XSUB(b.x)], 1u);
;         const unsigned gen = old / nloc;
;         if (old + 1u == (gen + 1u) * nloc) {
;             __builtin_amdgcn_fence(__ATOMIC_RELEASE, "agent");
;             asm volatile("s_waitcnt vmcnt(0)" ::: "memory");
;             const unsigned og = xb_add(&bar[XB_TOP], 1u);
;             const unsigned tg = og / nx;
;             if (og + 1u == (tg + 1u) * nx) xb_add(&bar[XB_TOPGEN], 1u);
;             else XB_SPIN(xb_ld(&bar[XB_TOPGEN]) == tg, bar);
;             __builtin_amdgcn_fence(__ATOMIC_ACQUIRE, "agent");
;             xb_add(&bar[XB_XGEN(b.x)], 1u);
;             asm volatile("s_waitcnt vmcnt(0)" ::: "memory");
;         } else {
;             XB_SPIN(xb_ld(&bar[XB_XGEN(b.x)]) == gen, bar);
.LBB0_310:
	s_or_b64 exec, exec, s[12:13]
	v_cvt_f32_u32_e32 v6, v4
	s_waitcnt vmcnt(0)
	v_readfirstlane_b32 s1, v5
	v_sub_u32_e32 v5, 0, v4
	v_rcp_iflag_f32_e32 v6, v6
	v_add_u32_e32 v7, s1, v3
	v_mul_f32_e32 v6, 0x4f7ffffe, v6
	v_cvt_u32_f32_e32 v6, v6
	v_mul_lo_u32 v3, v5, v6
	v_mul_hi_u32 v3, v6, v3
	v_add_u32_e32 v3, v6, v3
	v_mul_hi_u32 v3, v7, v3
	v_mul_lo_u32 v5, v3, v4
	v_sub_u32_e32 v5, v7, v5
	v_add_u32_e32 v6, 1, v3
	v_cmp_ge_u32_e32 vcc, v5, v4
	s_nop 1
	v_cndmask_b32_e32 v3, v3, v6, vcc
	v_sub_u32_e32 v6, v5, v4
	v_cndmask_b32_e32 v5, v5, v6, vcc
	v_add_u32_e32 v6, 1, v3
	v_cmp_ge_u32_e32 vcc, v5, v4
	v_add_u32_e32 v5, 1, v7
	s_nop 0
	v_cndmask_b32_e32 v3, v3, v6, vcc
	v_mul_lo_u32 v6, v4, v3
	v_add_u32_e32 v4, v6, v4
	v_cmp_ne_u32_e32 vcc, v5, v4
	s_and_saveexec_b64 s[2:3], vcc
	s_xor_b64 s[10:11], exec, s[2:3]
	s_cbranch_execz .LBB0_324
	s_waitcnt lgkmcnt(0)
	v_mov_b32_e32 v2, 0x2000
	s_load_dwordx2 s[16:17], s[90:91], 0xb0
	s_waitcnt lgkmcnt(0)
	s_add_u32 s16, s16, 0x1d79b500
	s_addc_u32 s17, s17, 0
	v_mov_b32_e32 v2, 0
	global_load_dword v2, v2, s[16:17] sc1
	s_waitcnt vmcnt(0)
	v_cmp_eq_u32_e32 vcc, v2, v3
	s_and_saveexec_b64 s[12:13], vcc
	s_cbranch_execz .LBB0_323
	s_add_u32 s14, s4, 0x1d798200
	s_addc_u32 s15, s5, 0
	s_mov_b32 s1, 1
	s_mov_b64 s[18:19], 0
	v_mov_b32_e32 v2, 0
	s_branch .LBB0_314

; __device__ __forceinline__ unsigned xb_ld(unsigned* p)              { return __hip_atomic_load(p, __ATOMIC_RELAXED, __HIP_MEMORY_SCOPE_AGENT); }
; __device__ __forceinline__ unsigned xb_add(unsigned* p, unsigned v) { return __hip_atomic_fetch_add(p, v, __ATOMIC_RELAXED, __HIP_MEMORY_SCOPE_AGENT); }
; #define XB_SPIN(cond, bar) do { unsigned _sp = 0; while (cond) { __builtin_amdgcn_s_sleep(1); \
;     if ((++_sp & 255u) == 0u) { if (xb_ld(&(bar)[XB_TMO])) break; if (_sp > XB_SPIN_CAP) { atomicAdd(&(bar)[XB_TMO], 1u); break; } } } } while (0)
; __device__ __forceinline__ void xcd_barrier(const XcdBarrier& b, const bool leader) {
;     ...
;         const unsigned old = xb_add(&bar[XB_XSUB(b.x)], 1u);
;         const unsigned gen = old / nloc;
;         if (old + 1u == (gen + 1u) * nloc) {
;             __builtin_amdgcn_fence(__ATOMIC_RELEASE, "agent");
;             asm volatile("s_waitcnt vmcnt(0)" ::: "memory");
;             const unsigned og = xb_add(&bar[XB_TOP], 1u);
;             const unsigned tg = og / nx;
;             if (og + 1u == (tg + 1u) * nx) xb_add(&bar[XB_TOPGEN], 1u);
;             else XB_SPIN(xb_ld(&bar[XB_TOPGEN]) == tg, bar);
;             __builtin_amdgcn_fence(__ATOMIC_ACQUIRE, "agent");
;             xb_add(&bar[XB_XGEN(b.x)], 1u);
;             asm volatile("s_waitcnt vmcnt(0)" ::: "memory");
;         } else {
;             XB_SPIN(xb_ld(&bar[XB_XGEN(b.x)]) == gen, bar);
.LBB0_470:
	s_or_b64 exec, exec, s[14:15]
	v_cvt_f32_u32_e32 v7, v5
	s_waitcnt vmcnt(0)
	v_readfirstlane_b32 s2, v6
	v_sub_u32_e32 v6, 0, v5
	v_rcp_iflag_f32_e32 v7, v7
	v_add_u32_e32 v8, s2, v2
	v_mul_f32_e32 v7, 0x4f7ffffe, v7
	v_cvt_u32_f32_e32 v7, v7
	v_mul_lo_u32 v2, v6, v7
	v_mul_hi_u32 v2, v7, v2
	v_add_u32_e32 v2, v7, v2
	v_mul_hi_u32 v2, v8, v2
	v_mul_lo_u32 v6, v2, v5
	v_sub_u32_e32 v6, v8, v6
	v_add_u32_e32 v7, 1, v2
	v_cmp_ge_u32_e32 vcc, v6, v5
	s_nop 1
	v_cndmask_b32_e32 v2, v2, v7, vcc
	v_sub_u32_e32 v7, v6, v5
	v_cndmask_b32_e32 v6, v6, v7, vcc
	v_add_u32_e32 v7, 1, v2
	v_cmp_ge_u32_e32 vcc, v6, v5
	v_add_u32_e32 v6, 1, v8
	s_nop 0
	v_cndmask_b32_e32 v2, v2, v7, vcc
	v_mul_lo_u32 v7, v5, v2
	v_add_u32_e32 v5, v7, v5
	v_cmp_ne_u32_e32 vcc, v6, v5
	s_and_saveexec_b64 s[2:3], vcc
	s_xor_b64 s[12:13], exec, s[2:3]
	s_cbranch_execz .LBB0_484
	s_waitcnt lgkmcnt(0)
	s_load_dwordx2 s[20:21], s[90:91], 0xb0
	s_waitcnt lgkmcnt(0)
	s_add_u32 s20, s20, 0x1d79b500
	s_addc_u32 s21, s21, 0
	v_mov_b32_e32 v4, 0
	global_load_dword v4, v4, s[20:21] sc1
	s_waitcnt vmcnt(0)
	v_cmp_eq_u32_e32 vcc, v4, v2
	s_and_saveexec_b64 s[14:15], vcc
	s_cbranch_execz .LBB0_483
	s_add_u32 s16, s18, 0x1d798200
	s_addc_u32 s17, s19, 0
	s_mov_b32 s2, 1
	s_mov_b64 s[22:23], 0
	s_branch .LBB0_474

; __device__ __forceinline__ unsigned xb_ld(unsigned* p)              { return __hip_atomic_load(p, __ATOMIC_RELAXED, __HIP_MEMORY_SCOPE_AGENT); }
; __device__ __forceinline__ unsigned xb_add(unsigned* p, unsigned v) { return __hip_atomic_fetch_add(p, v, __ATOMIC_RELAXED, __HIP_MEMORY_SCOPE_AGENT); }
; #define XB_SPIN(cond, bar) do { unsigned _sp = 0; while (cond) { __builtin_amdgcn_s_sleep(1); \
;     if ((++_sp & 255u) == 0u) { if (xb_ld(&(bar)[XB_TMO])) break; if (_sp > XB_SPIN_CAP) { atomicAdd(&(bar)[XB_TMO], 1u); break; } } } } while (0)
; __device__ __forceinline__ void xcd_barrier(const XcdBarrier& b, const bool leader) {
;     ...
;         const unsigned old = xb_add(&bar[XB_XSUB(b.x)], 1u);
;         const unsigned gen = old / nloc;
;         if (old + 1u == (gen + 1u) * nloc) {
;             __builtin_amdgcn_fence(__ATOMIC_RELEASE, "agent");
;             asm volatile("s_waitcnt vmcnt(0)" ::: "memory");
;             const unsigned og = xb_add(&bar[XB_TOP], 1u);
;             const unsigned tg = og / nx;
;             if (og + 1u == (tg + 1u) * nx) xb_add(&bar[XB_TOPGEN], 1u);
;             else XB_SPIN(xb_ld(&bar[XB_TOPGEN]) == tg, bar);
;             __builtin_amdgcn_fence(__ATOMIC_ACQUIRE, "agent");
;             xb_add(&bar[XB_XGEN(b.x)], 1u);
;             asm volatile("s_waitcnt vmcnt(0)" ::: "memory");
;         } else {
;             XB_SPIN(xb_ld(&bar[XB_XGEN(b.x)]) == gen, bar);
.LBB0_582:
	s_or_b64 exec, exec, s[12:13]
	v_cvt_f32_u32_e32 v7, v5
	s_waitcnt vmcnt(0)
	v_readfirstlane_b32 s2, v6
	v_sub_u32_e32 v6, 0, v5
	v_rcp_iflag_f32_e32 v7, v7
	v_add_u32_e32 v8, s2, v2
	v_mul_f32_e32 v7, 0x4f7ffffe, v7
	v_cvt_u32_f32_e32 v7, v7
	v_mul_lo_u32 v2, v6, v7
	v_mul_hi_u32 v2, v7, v2
	v_add_u32_e32 v2, v7, v2
	v_mul_hi_u32 v2, v8, v2
	v_mul_lo_u32 v6, v2, v5
	v_sub_u32_e32 v6, v8, v6
	v_add_u32_e32 v7, 1, v2
	v_cmp_ge_u32_e32 vcc, v6, v5
	s_nop 1
	v_cndmask_b32_e32 v2, v2, v7, vcc
	v_sub_u32_e32 v7, v6, v5
	v_cndmask_b32_e32 v6, v6, v7, vcc
	v_add_u32_e32 v7, 1, v2
	v_cmp_ge_u32_e32 vcc, v6, v5
	v_add_u32_e32 v6, 1, v8
	s_nop 0
	v_cndmask_b32_e32 v2, v2, v7, vcc
	v_mul_lo_u32 v7, v5, v2
	v_add_u32_e32 v5, v7, v5
	v_cmp_ne_u32_e32 vcc, v6, v5
	s_and_saveexec_b64 s[2:3], vcc
	s_xor_b64 s[10:11], exec, s[2:3]
	s_cbranch_execz .LBB0_596
	s_waitcnt lgkmcnt(0)
	s_load_dwordx2 s[16:17], s[90:91], 0xb0
	s_waitcnt lgkmcnt(0)
	s_add_u32 s16, s16, 0x1d79b500
	s_addc_u32 s17, s17, 0
	v_mov_b32_e32 v4, 0
	global_load_dword v4, v4, s[16:17] sc1
	s_waitcnt vmcnt(0)
	v_cmp_eq_u32_e32 vcc, v4, v2
	s_and_saveexec_b64 s[12:13], vcc
	s_cbranch_execz .LBB0_595
	s_add_u32 s14, s50, 0x1d798200
	s_addc_u32 s15, s51, 0
	s_mov_b32 s2, 1
	s_mov_b64 s[18:19], 0
	s_branch .LBB0_586

; __device__ __forceinline__ unsigned xb_ld(unsigned* p)              { return __hip_atomic_load(p, __ATOMIC_RELAXED, __HIP_MEMORY_SCOPE_AGENT); }
; __device__ __forceinline__ unsigned xb_add(unsigned* p, unsigned v) { return __hip_atomic_fetch_add(p, v, __ATOMIC_RELAXED, __HIP_MEMORY_SCOPE_AGENT); }
; #define XB_SPIN(cond, bar) do { unsigned _sp = 0; while (cond) { __builtin_amdgcn_s_sleep(1); \
;     if ((++_sp & 255u) == 0u) { if (xb_ld(&(bar)[XB_TMO])) break; if (_sp > XB_SPIN_CAP) { atomicAdd(&(bar)[XB_TMO], 1u); break; } } } } while (0)
; __device__ __forceinline__ void xcd_barrier(const XcdBarrier& b, const bool leader) {
;     ...
;         const unsigned old = xb_add(&bar[XB_XSUB(b.x)], 1u);
;         const unsigned gen = old / nloc;
;         if (old + 1u == (gen + 1u) * nloc) {
;             __builtin_amdgcn_fence(__ATOMIC_RELEASE, "agent");
;             asm volatile("s_waitcnt vmcnt(0)" ::: "memory");
;             const unsigned og = xb_add(&bar[XB_TOP], 1u);
;             const unsigned tg = og / nx;
;             if (og + 1u == (tg + 1u) * nx) xb_add(&bar[XB_TOPGEN], 1u);
;             else XB_SPIN(xb_ld(&bar[XB_TOPGEN]) == tg, bar);
;             __builtin_amdgcn_fence(__ATOMIC_ACQUIRE, "agent");
;             xb_add(&bar[XB_XGEN(b.x)], 1u);
;             asm volatile("s_waitcnt vmcnt(0)" ::: "memory");
;         } else {
;             XB_SPIN(xb_ld(&bar[XB_XGEN(b.x)]) == gen, bar);
.LBB0_660:
	s_or_b64 exec, exec, s[6:7]
	v_cvt_f32_u32_e32 v7, v5
	s_waitcnt vmcnt(0)
	v_readfirstlane_b32 s2, v6
	v_sub_u32_e32 v6, 0, v5
	v_rcp_iflag_f32_e32 v7, v7
	v_add_u32_e32 v8, s2, v2
	v_mul_f32_e32 v7, 0x4f7ffffe, v7
	v_cvt_u32_f32_e32 v7, v7
	v_mul_lo_u32 v2, v6, v7
	v_mul_hi_u32 v2, v7, v2
	v_add_u32_e32 v2, v7, v2
	v_mul_hi_u32 v2, v8, v2
	v_mul_lo_u32 v6, v2, v5
	v_sub_u32_e32 v6, v8, v6
	v_add_u32_e32 v7, 1, v2
	v_cmp_ge_u32_e32 vcc, v6, v5
	s_nop 1
	v_cndmask_b32_e32 v2, v2, v7, vcc
	v_sub_u32_e32 v7, v6, v5
	v_cndmask_b32_e32 v6, v6, v7, vcc
	v_add_u32_e32 v7, 1, v2
	v_cmp_ge_u32_e32 vcc, v6, v5
	v_add_u32_e32 v6, 1, v8
	s_nop 0
	v_cndmask_b32_e32 v2, v2, v7, vcc
	v_mul_lo_u32 v7, v5, v2
	v_add_u32_e32 v5, v7, v5
	v_cmp_ne_u32_e32 vcc, v6, v5
	s_and_saveexec_b64 s[2:3], vcc
	s_xor_b64 s[12:13], exec, s[2:3]
	s_cbranch_execz .LBB0_674
	s_waitcnt lgkmcnt(0)
	s_load_dwordx2 s[18:19], s[90:91], 0xb0
	s_waitcnt lgkmcnt(0)
	s_add_u32 s18, s18, 0x1d79b500
	s_addc_u32 s19, s19, 0
	v_mov_b32_e32 v4, 0
	global_load_dword v4, v4, s[18:19] sc1
	s_waitcnt vmcnt(0)
	v_cmp_eq_u32_e32 vcc, v4, v2
	s_and_saveexec_b64 s[14:15], vcc
	s_cbranch_execz .LBB0_673
	s_add_u32 s16, s4, 0x1d798200
	s_addc_u32 s17, s5, 0
	s_mov_b32 s2, 1
	s_mov_b64 s[20:21], 0
	s_branch .LBB0_664

; __device__ __forceinline__ unsigned xb_ld(unsigned* p)              { return __hip_atomic_load(p, __ATOMIC_RELAXED, __HIP_MEMORY_SCOPE_AGENT); }
; __device__ __forceinline__ unsigned xb_add(unsigned* p, unsigned v) { return __hip_atomic_fetch_add(p, v, __ATOMIC_RELAXED, __HIP_MEMORY_SCOPE_AGENT); }
; #define XB_SPIN(cond, bar) do { unsigned _sp = 0; while (cond) { __builtin_amdgcn_s_sleep(1); \
;     if ((++_sp & 255u) == 0u) { if (xb_ld(&(bar)[XB_TMO])) break; if (_sp > XB_SPIN_CAP) { atomicAdd(&(bar)[XB_TMO], 1u); break; } } } } while (0)
; __device__ __forceinline__ void xcd_barrier(const XcdBarrier& b, const bool leader) {
;     ...
;         const unsigned old = xb_add(&bar[XB_XSUB(b.x)], 1u);
;         const unsigned gen = old / nloc;
;         if (old + 1u == (gen + 1u) * nloc) {
;             __builtin_amdgcn_fence(__ATOMIC_RELEASE, "agent");
;             asm volatile("s_waitcnt vmcnt(0)" ::: "memory");
;             const unsigned og = xb_add(&bar[XB_TOP], 1u);
;             const unsigned tg = og / nx;
;             if (og + 1u == (tg + 1u) * nx) xb_add(&bar[XB_TOPGEN], 1u);
;             else XB_SPIN(xb_ld(&bar[XB_TOPGEN]) == tg, bar);
;             __builtin_amdgcn_fence(__ATOMIC_ACQUIRE, "agent");
;             xb_add(&bar[XB_XGEN(b.x)], 1u);
;             asm volatile("s_waitcnt vmcnt(0)" ::: "memory");
;         } else {
;             XB_SPIN(xb_ld(&bar[XB_XGEN(b.x)]) == gen, bar);
.LBB0_821:
	s_or_b64 exec, exec, s[6:7]
	v_cvt_f32_u32_e32 v7, v5
	s_waitcnt vmcnt(0)
	v_readfirstlane_b32 s2, v6
	v_sub_u32_e32 v6, 0, v5
	v_rcp_iflag_f32_e32 v7, v7
	v_add_u32_e32 v8, s2, v2
	v_mul_f32_e32 v7, 0x4f7ffffe, v7
	v_cvt_u32_f32_e32 v7, v7
	v_mul_lo_u32 v2, v6, v7
	v_mul_hi_u32 v2, v7, v2
	v_add_u32_e32 v2, v7, v2
	v_mul_hi_u32 v2, v8, v2
	v_mul_lo_u32 v6, v2, v5
	v_sub_u32_e32 v6, v8, v6
	v_add_u32_e32 v7, 1, v2
	v_cmp_ge_u32_e32 vcc, v6, v5
	s_nop 1
	v_cndmask_b32_e32 v2, v2, v7, vcc
	v_sub_u32_e32 v7, v6, v5
	v_cndmask_b32_e32 v6, v6, v7, vcc
	v_add_u32_e32 v7, 1, v2
	v_cmp_ge_u32_e32 vcc, v6, v5
	v_add_u32_e32 v6, 1, v8
	s_nop 0
	v_cndmask_b32_e32 v2, v2, v7, vcc
	v_mul_lo_u32 v7, v5, v2
	v_add_u32_e32 v5, v7, v5
	v_cmp_ne_u32_e32 vcc, v6, v5
	s_and_saveexec_b64 s[2:3], vcc
	s_xor_b64 s[16:17], exec, s[2:3]
	s_cbranch_execz .LBB0_835
	s_waitcnt lgkmcnt(0)
	s_load_dwordx2 s[22:23], s[90:91], 0xb0
	s_waitcnt lgkmcnt(0)
	s_add_u32 s22, s22, 0x1d79b500
	s_addc_u32 s23, s23, 0
	v_mov_b32_e32 v4, 0
	global_load_dword v4, v4, s[22:23] sc1
	s_waitcnt vmcnt(0)
	v_cmp_eq_u32_e32 vcc, v4, v2
	s_and_saveexec_b64 s[18:19], vcc
	s_cbranch_execz .LBB0_834
	s_add_u32 s20, s12, 0x1d798200
	s_addc_u32 s21, s13, 0
	s_mov_b32 s2, 1
	s_mov_b64 s[24:25], 0
	s_branch .LBB0_825

; __device__ __forceinline__ unsigned xb_ld(unsigned* p)              { return __hip_atomic_load(p, __ATOMIC_RELAXED, __HIP_MEMORY_SCOPE_AGENT); }
; __device__ __forceinline__ unsigned xb_add(unsigned* p, unsigned v) { return __hip_atomic_fetch_add(p, v, __ATOMIC_RELAXED, __HIP_MEMORY_SCOPE_AGENT); }
; #define XB_SPIN(cond, bar) do { unsigned _sp = 0; while (cond) { __builtin_amdgcn_s_sleep(1); \
;     if ((++_sp & 255u) == 0u) { if (xb_ld(&(bar)[XB_TMO])) break; if (_sp > XB_SPIN_CAP) { atomicAdd(&(bar)[XB_TMO], 1u); break; } } } } while (0)
; __device__ __forceinline__ void xcd_barrier(const XcdBarrier& b, const bool leader) {
;     ...
;         const unsigned old = xb_add(&bar[XB_XSUB(b.x)], 1u);
;         const unsigned gen = old / nloc;
;         if (old + 1u == (gen + 1u) * nloc) {
;             __builtin_amdgcn_fence(__ATOMIC_RELEASE, "agent");
;             asm volatile("s_waitcnt vmcnt(0)" ::: "memory");
;             const unsigned og = xb_add(&bar[XB_TOP], 1u);
;             const unsigned tg = og / nx;
;             if (og + 1u == (tg + 1u) * nx) xb_add(&bar[XB_TOPGEN], 1u);
;             else XB_SPIN(xb_ld(&bar[XB_TOPGEN]) == tg, bar);
;             __builtin_amdgcn_fence(__ATOMIC_ACQUIRE, "agent");
;             xb_add(&bar[XB_XGEN(b.x)], 1u);
;             asm volatile("s_waitcnt vmcnt(0)" ::: "memory");
;         } else {
;             XB_SPIN(xb_ld(&bar[XB_XGEN(b.x)]) == gen, bar);
.LBB0_1030:
	s_or_b64 exec, exec, s[6:7]
	v_cvt_f32_u32_e32 v7, v5
	s_waitcnt vmcnt(0)
	v_readfirstlane_b32 s2, v6
	v_sub_u32_e32 v6, 0, v5
	v_rcp_iflag_f32_e32 v7, v7
	v_add_u32_e32 v8, s2, v2
	v_mul_f32_e32 v7, 0x4f7ffffe, v7
	v_cvt_u32_f32_e32 v7, v7
	v_mul_lo_u32 v2, v6, v7
	v_mul_hi_u32 v2, v7, v2
	v_add_u32_e32 v2, v7, v2
	v_mul_hi_u32 v2, v8, v2
	v_mul_lo_u32 v6, v2, v5
	v_sub_u32_e32 v6, v8, v6
	v_add_u32_e32 v7, 1, v2
	v_cmp_ge_u32_e32 vcc, v6, v5
	s_nop 1
	v_cndmask_b32_e32 v2, v2, v7, vcc
	v_sub_u32_e32 v7, v6, v5
	v_cndmask_b32_e32 v6, v6, v7, vcc
	v_add_u32_e32 v7, 1, v2
	v_cmp_ge_u32_e32 vcc, v6, v5
	v_add_u32_e32 v6, 1, v8
	s_nop 0
	v_cndmask_b32_e32 v2, v2, v7, vcc
	v_mul_lo_u32 v7, v5, v2
	v_add_u32_e32 v5, v7, v5
	v_cmp_ne_u32_e32 vcc, v6, v5
	s_and_saveexec_b64 s[2:3], vcc
	s_xor_b64 s[12:13], exec, s[2:3]
	s_cbranch_execz .LBB0_1044
	s_waitcnt lgkmcnt(0)
	s_load_dwordx2 s[20:21], s[90:91], 0xb0
	s_waitcnt lgkmcnt(0)
	s_add_u32 s20, s20, 0x1d79b500
	s_addc_u32 s21, s21, 0
	v_mov_b32_e32 v4, 0
	global_load_dword v4, v4, s[20:21] sc1
	s_waitcnt vmcnt(0)
	v_cmp_eq_u32_e32 vcc, v4, v2
	s_and_saveexec_b64 s[14:15], vcc
	s_cbranch_execz .LBB0_1043
	s_add_u32 s16, s18, 0x1d798200
	s_addc_u32 s17, s19, 0
	s_mov_b32 s2, 1
	s_mov_b64 s[22:23], 0
	s_branch .LBB0_1034

; __device__ __forceinline__ unsigned xb_ld(unsigned* p)              { return __hip_atomic_load(p, __ATOMIC_RELAXED, __HIP_MEMORY_SCOPE_AGENT); }
; __device__ __forceinline__ unsigned xb_add(unsigned* p, unsigned v) { return __hip_atomic_fetch_add(p, v, __ATOMIC_RELAXED, __HIP_MEMORY_SCOPE_AGENT); }
; #define XB_SPIN(cond, bar) do { unsigned _sp = 0; while (cond) { __builtin_amdgcn_s_sleep(1); \
;     if ((++_sp & 255u) == 0u) { if (xb_ld(&(bar)[XB_TMO])) break; if (_sp > XB_SPIN_CAP) { atomicAdd(&(bar)[XB_TMO], 1u); break; } } } } while (0)
; __device__ __forceinline__ void xcd_barrier(const XcdBarrier& b, const bool leader) {
;     ...
;         const unsigned old = xb_add(&bar[XB_XSUB(b.x)], 1u);
;         const unsigned gen = old / nloc;
;         if (old + 1u == (gen + 1u) * nloc) {
;             __builtin_amdgcn_fence(__ATOMIC_RELEASE, "agent");
;             asm volatile("s_waitcnt vmcnt(0)" ::: "memory");
;             const unsigned og = xb_add(&bar[XB_TOP], 1u);
;             const unsigned tg = og / nx;
;             if (og + 1u == (tg + 1u) * nx) xb_add(&bar[XB_TOPGEN], 1u);
;             else XB_SPIN(xb_ld(&bar[XB_TOPGEN]) == tg, bar);
;             __builtin_amdgcn_fence(__ATOMIC_ACQUIRE, "agent");
;             xb_add(&bar[XB_XGEN(b.x)], 1u);
;             asm volatile("s_waitcnt vmcnt(0)" ::: "memory");
;         } else {
;             XB_SPIN(xb_ld(&bar[XB_XGEN(b.x)]) == gen, bar);
.LBB0_1115:
	s_or_b64 exec, exec, s[12:13]
	v_cvt_f32_u32_e32 v4, v2
	s_waitcnt vmcnt(0)
	v_readfirstlane_b32 s0, v3
	v_sub_u32_e32 v3, 0, v2
	v_rcp_iflag_f32_e32 v4, v4
	v_add_u32_e32 v5, s0, v1
	v_mul_f32_e32 v4, 0x4f7ffffe, v4
	v_cvt_u32_f32_e32 v4, v4
	v_mul_lo_u32 v1, v3, v4
	v_mul_hi_u32 v1, v4, v1
	v_add_u32_e32 v1, v4, v1
	v_mul_hi_u32 v1, v5, v1
	v_mul_lo_u32 v3, v1, v2
	v_sub_u32_e32 v3, v5, v3
	v_add_u32_e32 v4, 1, v1
	v_cmp_ge_u32_e32 vcc, v3, v2
	s_nop 1
	v_cndmask_b32_e32 v1, v1, v4, vcc
	v_sub_u32_e32 v4, v3, v2
	v_cndmask_b32_e32 v3, v3, v4, vcc
	v_add_u32_e32 v4, 1, v1
	v_cmp_ge_u32_e32 vcc, v3, v2
	v_add_u32_e32 v3, 1, v5
	s_nop 0
	v_cndmask_b32_e32 v1, v1, v4, vcc
	v_mul_lo_u32 v4, v2, v1
	v_add_u32_e32 v2, v4, v2
	v_cmp_ne_u32_e32 vcc, v3, v2
	s_and_saveexec_b64 s[0:1], vcc
	s_xor_b64 s[10:11], exec, s[0:1]
	s_cbranch_execz .LBB0_1129
	s_waitcnt lgkmcnt(0)
	v_mov_b32_e32 v0, 0x2000
	s_load_dwordx2 s[16:17], s[90:91], 0xb0
	s_waitcnt lgkmcnt(0)
	s_add_u32 s16, s16, 0x1d79b500
	s_addc_u32 s17, s17, 0
	v_mov_b32_e32 v0, 0
	global_load_dword v0, v0, s[16:17] sc1
	s_waitcnt vmcnt(0)
	v_cmp_eq_u32_e32 vcc, v0, v1
	s_and_saveexec_b64 s[12:13], vcc
	s_cbranch_execz .LBB0_1128
	s_add_u32 s14, s18, 0x1d798200
	s_addc_u32 s15, s19, 0
	s_mov_b32 s0, 1
	s_mov_b64 s[20:21], 0
	v_mov_b32_e32 v0, 0
	s_branch .LBB0_1119

; __device__ __forceinline__ unsigned xb_ld(unsigned* p)              { return __hip_atomic_load(p, __ATOMIC_RELAXED, __HIP_MEMORY_SCOPE_AGENT); }
; __device__ __forceinline__ unsigned xb_add(unsigned* p, unsigned v) { return __hip_atomic_fetch_add(p, v, __ATOMIC_RELAXED, __HIP_MEMORY_SCOPE_AGENT); }
; #define XB_SPIN(cond, bar) do { unsigned _sp = 0; while (cond) { __builtin_amdgcn_s_sleep(1); \
;     if ((++_sp & 255u) == 0u) { if (xb_ld(&(bar)[XB_TMO])) break; if (_sp > XB_SPIN_CAP) { atomicAdd(&(bar)[XB_TMO], 1u); break; } } } } while (0)
; __device__ __forceinline__ void xcd_barrier(const XcdBarrier& b, const bool leader) {
;     ...
;         const unsigned old = xb_add(&bar[XB_XSUB(b.x)], 1u);
;         const unsigned gen = old / nloc;
;         if (old + 1u == (gen + 1u) * nloc) {
;             __builtin_amdgcn_fence(__ATOMIC_RELEASE, "agent");
;             asm volatile("s_waitcnt vmcnt(0)" ::: "memory");
;             const unsigned og = xb_add(&bar[XB_TOP], 1u);
;             const unsigned tg = og / nx;
;             if (og + 1u == (tg + 1u) * nx) xb_add(&bar[XB_TOPGEN], 1u);
;             else XB_SPIN(xb_ld(&bar[XB_TOPGEN]) == tg, bar);
;             __builtin_amdgcn_fence(__ATOMIC_ACQUIRE, "agent");
;             xb_add(&bar[XB_XGEN(b.x)], 1u);
;             asm volatile("s_waitcnt vmcnt(0)" ::: "memory");
;         } else {
;             XB_SPIN(xb_ld(&bar[XB_XGEN(b.x)]) == gen, bar);
.LBB0_1198:
	s_or_b64 exec, exec, s[10:11]
	v_cvt_f32_u32_e32 v4, v2
	s_waitcnt vmcnt(0)
	v_readfirstlane_b32 s0, v3
	v_sub_u32_e32 v3, 0, v2
	v_rcp_iflag_f32_e32 v4, v4
	v_add_u32_e32 v5, s0, v1
	v_mul_f32_e32 v4, 0x4f7ffffe, v4
	v_cvt_u32_f32_e32 v4, v4
	v_mul_lo_u32 v1, v3, v4
	v_mul_hi_u32 v1, v4, v1
	v_add_u32_e32 v1, v4, v1
	v_mul_hi_u32 v1, v5, v1
	v_mul_lo_u32 v3, v1, v2
	v_sub_u32_e32 v3, v5, v3
	v_add_u32_e32 v4, 1, v1
	v_cmp_ge_u32_e32 vcc, v3, v2
	s_nop 1
	v_cndmask_b32_e32 v1, v1, v4, vcc
	v_sub_u32_e32 v4, v3, v2
	v_cndmask_b32_e32 v3, v3, v4, vcc
	v_add_u32_e32 v4, 1, v1
	v_cmp_ge_u32_e32 vcc, v3, v2
	v_add_u32_e32 v3, 1, v5
	s_nop 0
	v_cndmask_b32_e32 v1, v1, v4, vcc
	v_mul_lo_u32 v4, v2, v1
	v_add_u32_e32 v2, v4, v2
	v_cmp_ne_u32_e32 vcc, v3, v2
	s_and_saveexec_b64 s[0:1], vcc
	s_xor_b64 s[8:9], exec, s[0:1]
	s_cbranch_execz .LBB0_1212
	s_waitcnt lgkmcnt(0)
	v_mov_b32_e32 v0, 0x2000
	s_load_dwordx2 s[14:15], s[90:91], 0xb0
	s_waitcnt lgkmcnt(0)
	s_add_u32 s14, s14, 0x1d79b500
	s_addc_u32 s15, s15, 0
	v_mov_b32_e32 v0, 0
	global_load_dword v0, v0, s[14:15] sc1
	s_waitcnt vmcnt(0)
	v_cmp_eq_u32_e32 vcc, v0, v1
	s_and_saveexec_b64 s[10:11], vcc
	s_cbranch_execz .LBB0_1211
	s_add_u32 s12, s4, 0x1d798200
	s_addc_u32 s13, s5, 0
	s_mov_b32 s0, 1
	s_mov_b64 s[16:17], 0
	v_mov_b32_e32 v0, 0
	s_branch .LBB0_1202
